# S5 MFMA groups: counted lgkmcnt waits placed at the first consuming MFMA quarter, post-group pad trimmed to the required 4 wait states
# baseline (speedup 1.0000x reference)
; #define LAS __attribute__((address_space(3)))
; __device__ __forceinline__ unsigned f2bf(float f) { unsigned u = __builtin_bit_cast(unsigned, f); return (u + 0x7fffu + ((u >> 16) & 1u)) >> 16; }
; __device__ __forceinline__ void s5_phase(LAS unsigned char* lds, const unsigned char* ws, const bf16_t* proj, const float* c_re, const float* c_im, const float* dskip, bf16_t* z,
;                                          int vcu, int G, int wave, int lane) {
;     ...
; #pragma unroll
;             for (int k = 0; k < 32; ++k) {
;                 f32x2 xa = (f32x2){0.f, 0.f}, xb = (f32x2){0.f, 0.f};
; #pragma unroll
;                 for (int q = 0; q < 4; ++q) { const f32x4 u4 = *(const LAS f32x4*)(Uc + k * 16 + 4 * q);
;                     xa = __builtin_elementwise_fma((f32x2){u4[0], u4[0]}, (f32x2){bbre[4 * q], bbim[4 * q]}, xa);
;                     xb = __builtin_elementwise_fma((f32x2){u4[1], u4[1]}, (f32x2){bbre[4 * q + 1], bbim[4 * q + 1]}, xb);
;                     xa = __builtin_elementwise_fma((f32x2){u4[2], u4[2]}, (f32x2){bbre[4 * q + 2], bbim[4 * q + 2]}, xa);
;                     xb = __builtin_elementwise_fma((f32x2){u4[3], u4[3]}, (f32x2){bbre[4 * q + 3], bbim[4 * q + 3]}, xb); }
;                 const f32x2 xx = xa + xb;
;                 const float nr = are * hre - aim * him + xx[0], ni = are * him + aim * hre + xx[1]; hre = nr; him = ni;
;                 Hc[k * 136 + n] = (bf16_t)f2bf(hre); Hc[k * 136 + 64 + n] = (bf16_t)f2bf(him);
.LBB0_386:
	s_or_b64 exec, exec, s[0:1]
	s_waitcnt vmcnt(19)
	v_mov_b32_e32 v40, s14
	v_and_b32_e32 v248, 3, v193
	v_lshl_add_u32 v248, v248, 6, v40
	s_waitcnt vmcnt(18)
	ds_read_b128 v[216:219], v248 offset:0
	ds_read_b128 v[220:223], v248 offset:16
	ds_read_b128 v[224:227], v248 offset:32
	ds_read_b128 v[228:231], v248 offset:48
	s_waitcnt lgkmcnt(3)
	v_mfma_f32_4x4x1_16b_f32 v[232:235], v216, v64, 0
	v_mfma_f32_4x4x1_16b_f32 v[236:239], v216, v65, 0
	v_mfma_f32_4x4x1_16b_f32 v[240:243], v217, v12, 0
	v_mfma_f32_4x4x1_16b_f32 v[244:247], v217, v13, 0
	v_mfma_f32_4x4x1_16b_f32 v[232:235], v218, v66, v[232:235]
	v_mfma_f32_4x4x1_16b_f32 v[236:239], v218, v67, v[236:239]
	v_mfma_f32_4x4x1_16b_f32 v[240:243], v219, v14, v[240:243]
	v_mfma_f32_4x4x1_16b_f32 v[244:247], v219, v15, v[244:247]
	s_waitcnt lgkmcnt(2)
	v_mfma_f32_4x4x1_16b_f32 v[232:235], v220, v68, v[232:235]
	v_mfma_f32_4x4x1_16b_f32 v[236:239], v220, v69, v[236:239]
	v_mfma_f32_4x4x1_16b_f32 v[240:243], v221, v8, v[240:243]
	v_mfma_f32_4x4x1_16b_f32 v[244:247], v221, v9, v[244:247]
	v_mfma_f32_4x4x1_16b_f32 v[232:235], v222, v70, v[232:235]
	v_mfma_f32_4x4x1_16b_f32 v[236:239], v222, v71, v[236:239]
	v_mfma_f32_4x4x1_16b_f32 v[240:243], v223, v10, v[240:243]
	v_mfma_f32_4x4x1_16b_f32 v[244:247], v223, v11, v[244:247]
	s_waitcnt lgkmcnt(1)
	v_mfma_f32_4x4x1_16b_f32 v[232:235], v224, v72, v[232:235]
	v_mfma_f32_4x4x1_16b_f32 v[236:239], v224, v73, v[236:239]
	v_mfma_f32_4x4x1_16b_f32 v[240:243], v225, v4, v[240:243]
	v_mfma_f32_4x4x1_16b_f32 v[244:247], v225, v5, v[244:247]
	v_mfma_f32_4x4x1_16b_f32 v[232:235], v226, v74, v[232:235]
	v_mfma_f32_4x4x1_16b_f32 v[236:239], v226, v75, v[236:239]
	v_mfma_f32_4x4x1_16b_f32 v[240:243], v227, v6, v[240:243]
	v_mfma_f32_4x4x1_16b_f32 v[244:247], v227, v7, v[244:247]
	s_waitcnt lgkmcnt(0)
	v_mfma_f32_4x4x1_16b_f32 v[232:235], v228, v76, v[232:235]
	v_mfma_f32_4x4x1_16b_f32 v[236:239], v228, v77, v[236:239]
	v_mfma_f32_4x4x1_16b_f32 v[240:243], v229, v0, v[240:243]
	v_mfma_f32_4x4x1_16b_f32 v[244:247], v229, v1, v[244:247]
	v_mfma_f32_4x4x1_16b_f32 v[232:235], v230, v78, v[232:235]
	v_mfma_f32_4x4x1_16b_f32 v[236:239], v230, v79, v[236:239]
	v_mfma_f32_4x4x1_16b_f32 v[240:243], v231, v2, v[240:243]
	v_mfma_f32_4x4x1_16b_f32 v[244:247], v231, v3, v[244:247]
	s_nop 2
	s_waitcnt vmcnt(13)
	v_lshlrev_b32_e32 v108, 16, v108
	v_add_f32_e32 v42, v240, v232
	v_add_f32_e32 v43, v244, v236
	v_mul_f32_e32 v44, v61, v87
	v_pk_fma_f32 v[44:45], v[60:61], v[86:87], v[44:45] op_sel_hi:[1,1,0] neg_lo:[0,0,1] neg_hi:[0,0,1]
	s_nop 0
	v_pk_add_f32 v[46:47], v[44:45], v[42:43]
	v_mov_b32_e32 v44, v87
	v_pk_mul_f32 v[44:45], v[60:61], v[44:45]
	v_pk_fma_f32 v[44:45], v[50:51], v[86:87], v[44:45]
	v_pk_add_f32 v[86:87], v[44:45], v[42:43] op_sel:[0,1] op_sel_hi:[1,0]
	v_cvt_pk_bf16_f32 v41, v46, v86
	ds_write_b16 v88, v41
	ds_write_b16_d16_hi v88, v41 offset:128
	v_add_f32_e32 v42, v241, v233
	v_add_f32_e32 v43, v245, v237
	v_pk_mul_f32 v[44:45], v[50:51], v[86:87]
	s_nop 0
	v_pk_fma_f32 v[44:45], v[60:61], v[46:47], v[44:45] neg_lo:[0,0,1] neg_hi:[0,0,1]
	s_nop 0
	v_pk_add_f32 v[134:135], v[44:45], v[42:43]
	v_pk_mul_f32 v[44:45], v[50:51], v[46:47]
	v_pk_fma_f32 v[44:45], v[60:61], v[86:87], v[44:45]
	v_pk_add_f32 v[46:47], v[44:45], v[42:43] op_sel:[0,1] op_sel_hi:[1,0]
	v_cvt_pk_bf16_f32 v41, v134, v46
	ds_write_b16 v88, v41 offset:272
	ds_write_b16_d16_hi v88, v41 offset:400
	v_add_f32_e32 v42, v242, v234
	v_add_f32_e32 v43, v246, v238
	v_pk_mul_f32 v[44:45], v[50:51], v[46:47]
	s_nop 0
	v_pk_fma_f32 v[44:45], v[60:61], v[134:135], v[44:45] neg_lo:[0,0,1] neg_hi:[0,0,1]
	s_nop 0
	v_pk_add_f32 v[86:87], v[44:45], v[42:43]
	v_pk_mul_f32 v[44:45], v[50:51], v[134:135]
	v_pk_fma_f32 v[44:45], v[60:61], v[46:47], v[44:45]
	v_pk_add_f32 v[46:47], v[44:45], v[42:43] op_sel:[0,1] op_sel_hi:[1,0]
	v_cvt_pk_bf16_f32 v41, v86, v46
	ds_write_b16 v88, v41 offset:544
	ds_write_b16_d16_hi v88, v41 offset:672
	v_add_f32_e32 v42, v243, v235
	v_add_f32_e32 v43, v247, v239
	v_pk_mul_f32 v[44:45], v[50:51], v[46:47]
	s_nop 0
	v_pk_fma_f32 v[44:45], v[60:61], v[86:87], v[44:45] neg_lo:[0,0,1] neg_hi:[0,0,1]
	s_nop 0
	v_pk_add_f32 v[134:135], v[44:45], v[42:43]
	v_pk_mul_f32 v[44:45], v[50:51], v[86:87]
	v_pk_fma_f32 v[44:45], v[60:61], v[46:47], v[44:45]
	v_pk_add_f32 v[46:47], v[44:45], v[42:43] op_sel:[0,1] op_sel_hi:[1,0]
	v_cvt_pk_bf16_f32 v41, v134, v46
	ds_write_b16 v88, v41 offset:816
	ds_write_b16_d16_hi v88, v41 offset:944
	ds_read_b128 v[216:219], v248 offset:256
	ds_read_b128 v[220:223], v248 offset:272
	ds_read_b128 v[224:227], v248 offset:288
	ds_read_b128 v[228:231], v248 offset:304
	s_waitcnt lgkmcnt(3)
	v_mfma_f32_4x4x1_16b_f32 v[232:235], v216, v64, 0
	v_mfma_f32_4x4x1_16b_f32 v[236:239], v216, v65, 0
	v_mfma_f32_4x4x1_16b_f32 v[240:243], v217, v12, 0
	v_mfma_f32_4x4x1_16b_f32 v[244:247], v217, v13, 0
	v_mfma_f32_4x4x1_16b_f32 v[232:235], v218, v66, v[232:235]
	v_mfma_f32_4x4x1_16b_f32 v[236:239], v218, v67, v[236:239]
	v_mfma_f32_4x4x1_16b_f32 v[240:243], v219, v14, v[240:243]
	v_mfma_f32_4x4x1_16b_f32 v[244:247], v219, v15, v[244:247]
	s_waitcnt lgkmcnt(2)
	v_mfma_f32_4x4x1_16b_f32 v[232:235], v220, v68, v[232:235]
	v_mfma_f32_4x4x1_16b_f32 v[236:239], v220, v69, v[236:239]
	v_mfma_f32_4x4x1_16b_f32 v[240:243], v221, v8, v[240:243]
	v_mfma_f32_4x4x1_16b_f32 v[244:247], v221, v9, v[244:247]
	v_mfma_f32_4x4x1_16b_f32 v[232:235], v222, v70, v[232:235]
	v_mfma_f32_4x4x1_16b_f32 v[236:239], v222, v71, v[236:239]
	v_mfma_f32_4x4x1_16b_f32 v[240:243], v223, v10, v[240:243]
	v_mfma_f32_4x4x1_16b_f32 v[244:247], v223, v11, v[244:247]
	s_waitcnt lgkmcnt(1)
; #define LAS __attribute__((address_space(3)))
; __device__ __forceinline__ unsigned f2bf(float f) { unsigned u = __builtin_bit_cast(unsigned, f); return (u + 0x7fffu + ((u >> 16) & 1u)) >> 16; }
; __device__ __forceinline__ void s5_phase(LAS unsigned char* lds, const unsigned char* ws, const bf16_t* proj, const float* c_re, const float* c_im, const float* dskip, bf16_t* z,
;                                          int vcu, int G, int wave, int lane) {
;     ...
;             for (int k = 0; k < 32; ++k) {
;                 f32x2 xa = (f32x2){0.f, 0.f}, xb = (f32x2){0.f, 0.f};
; #pragma unroll
;                 for (int q = 0; q < 4; ++q) { const f32x4 u4 = *(const LAS f32x4*)(Uc + k * 16 + 4 * q);
;                     xa = __builtin_elementwise_fma((f32x2){u4[0], u4[0]}, (f32x2){bbre[4 * q], bbim[4 * q]}, xa);
;                     xb = __builtin_elementwise_fma((f32x2){u4[1], u4[1]}, (f32x2){bbre[4 * q + 1], bbim[4 * q + 1]}, xb);
;                     xa = __builtin_elementwise_fma((f32x2){u4[2], u4[2]}, (f32x2){bbre[4 * q + 2], bbim[4 * q + 2]}, xa);
;                     xb = __builtin_elementwise_fma((f32x2){u4[3], u4[3]}, (f32x2){bbre[4 * q + 3], bbim[4 * q + 3]}, xb); }
;                 const f32x2 xx = xa + xb;
;                 const float nr = are * hre - aim * him + xx[0], ni = are * him + aim * hre + xx[1]; hre = nr; him = ni;
;                 Hc[k * 136 + n] = (bf16_t)f2bf(hre); Hc[k * 136 + 64 + n] = (bf16_t)f2bf(him);
	v_mfma_f32_4x4x1_16b_f32 v[232:235], v224, v72, v[232:235]
	v_mfma_f32_4x4x1_16b_f32 v[236:239], v224, v73, v[236:239]
	v_mfma_f32_4x4x1_16b_f32 v[240:243], v225, v4, v[240:243]
	v_mfma_f32_4x4x1_16b_f32 v[244:247], v225, v5, v[244:247]
	v_mfma_f32_4x4x1_16b_f32 v[232:235], v226, v74, v[232:235]
	v_mfma_f32_4x4x1_16b_f32 v[236:239], v226, v75, v[236:239]
	v_mfma_f32_4x4x1_16b_f32 v[240:243], v227, v6, v[240:243]
	v_mfma_f32_4x4x1_16b_f32 v[244:247], v227, v7, v[244:247]
	s_waitcnt lgkmcnt(0)
	v_mfma_f32_4x4x1_16b_f32 v[232:235], v228, v76, v[232:235]
	v_mfma_f32_4x4x1_16b_f32 v[236:239], v228, v77, v[236:239]
	v_mfma_f32_4x4x1_16b_f32 v[240:243], v229, v0, v[240:243]
	v_mfma_f32_4x4x1_16b_f32 v[244:247], v229, v1, v[244:247]
	v_mfma_f32_4x4x1_16b_f32 v[232:235], v230, v78, v[232:235]
	v_mfma_f32_4x4x1_16b_f32 v[236:239], v230, v79, v[236:239]
	v_mfma_f32_4x4x1_16b_f32 v[240:243], v231, v2, v[240:243]
	v_mfma_f32_4x4x1_16b_f32 v[244:247], v231, v3, v[244:247]
	s_nop 2
	v_add_f32_e32 v42, v240, v232
	v_add_f32_e32 v43, v244, v236
	v_pk_mul_f32 v[44:45], v[50:51], v[46:47]
	s_nop 0
	v_pk_fma_f32 v[44:45], v[60:61], v[134:135], v[44:45] neg_lo:[0,0,1] neg_hi:[0,0,1]
	s_nop 0
	v_pk_add_f32 v[86:87], v[44:45], v[42:43]
	v_pk_mul_f32 v[44:45], v[50:51], v[134:135]
	v_pk_fma_f32 v[44:45], v[60:61], v[46:47], v[44:45]
	v_pk_add_f32 v[46:47], v[44:45], v[42:43] op_sel:[0,1] op_sel_hi:[1,0]
	v_cvt_pk_bf16_f32 v41, v86, v46
	ds_write_b16 v88, v41 offset:1088
	ds_write_b16_d16_hi v88, v41 offset:1216
	v_add_f32_e32 v42, v241, v233
	v_add_f32_e32 v43, v245, v237
	v_pk_mul_f32 v[44:45], v[50:51], v[46:47]
	s_nop 0
	v_pk_fma_f32 v[44:45], v[60:61], v[86:87], v[44:45] neg_lo:[0,0,1] neg_hi:[0,0,1]
	s_nop 0
	v_pk_add_f32 v[134:135], v[44:45], v[42:43]
	v_pk_mul_f32 v[44:45], v[50:51], v[86:87]
	v_pk_fma_f32 v[44:45], v[60:61], v[46:47], v[44:45]
	v_pk_add_f32 v[46:47], v[44:45], v[42:43] op_sel:[0,1] op_sel_hi:[1,0]
	v_cvt_pk_bf16_f32 v41, v134, v46
	ds_write_b16 v88, v41 offset:1360
	ds_write_b16_d16_hi v88, v41 offset:1488
	v_add_f32_e32 v42, v242, v234
	v_add_f32_e32 v43, v246, v238
	v_pk_mul_f32 v[44:45], v[50:51], v[46:47]
	s_nop 0
	v_pk_fma_f32 v[44:45], v[60:61], v[134:135], v[44:45] neg_lo:[0,0,1] neg_hi:[0,0,1]
	s_nop 0
	v_pk_add_f32 v[86:87], v[44:45], v[42:43]
	v_pk_mul_f32 v[44:45], v[50:51], v[134:135]
	v_pk_fma_f32 v[44:45], v[60:61], v[46:47], v[44:45]
	v_pk_add_f32 v[46:47], v[44:45], v[42:43] op_sel:[0,1] op_sel_hi:[1,0]
	v_cvt_pk_bf16_f32 v41, v86, v46
	ds_write_b16 v88, v41 offset:1632
	ds_write_b16_d16_hi v88, v41 offset:1760
	v_add_f32_e32 v42, v243, v235
	v_add_f32_e32 v43, v247, v239
	v_pk_mul_f32 v[44:45], v[50:51], v[46:47]
	s_nop 0
	v_pk_fma_f32 v[44:45], v[60:61], v[86:87], v[44:45] neg_lo:[0,0,1] neg_hi:[0,0,1]
	s_nop 0
	v_pk_add_f32 v[134:135], v[44:45], v[42:43]
	v_pk_mul_f32 v[44:45], v[50:51], v[86:87]
	v_pk_fma_f32 v[44:45], v[60:61], v[46:47], v[44:45]
	v_pk_add_f32 v[46:47], v[44:45], v[42:43] op_sel:[0,1] op_sel_hi:[1,0]
	v_cvt_pk_bf16_f32 v41, v134, v46
	ds_write_b16 v88, v41 offset:1904
	ds_write_b16_d16_hi v88, v41 offset:2032
	ds_read_b128 v[216:219], v248 offset:512
	ds_read_b128 v[220:223], v248 offset:528
	ds_read_b128 v[224:227], v248 offset:544
	ds_read_b128 v[228:231], v248 offset:560
	s_waitcnt lgkmcnt(3)
	v_mfma_f32_4x4x1_16b_f32 v[232:235], v216, v64, 0
	v_mfma_f32_4x4x1_16b_f32 v[236:239], v216, v65, 0
	v_mfma_f32_4x4x1_16b_f32 v[240:243], v217, v12, 0
	v_mfma_f32_4x4x1_16b_f32 v[244:247], v217, v13, 0
	v_mfma_f32_4x4x1_16b_f32 v[232:235], v218, v66, v[232:235]
	v_mfma_f32_4x4x1_16b_f32 v[236:239], v218, v67, v[236:239]
	v_mfma_f32_4x4x1_16b_f32 v[240:243], v219, v14, v[240:243]
	v_mfma_f32_4x4x1_16b_f32 v[244:247], v219, v15, v[244:247]
	s_waitcnt lgkmcnt(2)
	v_mfma_f32_4x4x1_16b_f32 v[232:235], v220, v68, v[232:235]
	v_mfma_f32_4x4x1_16b_f32 v[236:239], v220, v69, v[236:239]
	v_mfma_f32_4x4x1_16b_f32 v[240:243], v221, v8, v[240:243]
	v_mfma_f32_4x4x1_16b_f32 v[244:247], v221, v9, v[244:247]
	v_mfma_f32_4x4x1_16b_f32 v[232:235], v222, v70, v[232:235]
	v_mfma_f32_4x4x1_16b_f32 v[236:239], v222, v71, v[236:239]
	v_mfma_f32_4x4x1_16b_f32 v[240:243], v223, v10, v[240:243]
	v_mfma_f32_4x4x1_16b_f32 v[244:247], v223, v11, v[244:247]
	s_waitcnt lgkmcnt(1)
	v_mfma_f32_4x4x1_16b_f32 v[232:235], v224, v72, v[232:235]
	v_mfma_f32_4x4x1_16b_f32 v[236:239], v224, v73, v[236:239]
	v_mfma_f32_4x4x1_16b_f32 v[240:243], v225, v4, v[240:243]
	v_mfma_f32_4x4x1_16b_f32 v[244:247], v225, v5, v[244:247]
	v_mfma_f32_4x4x1_16b_f32 v[232:235], v226, v74, v[232:235]
	v_mfma_f32_4x4x1_16b_f32 v[236:239], v226, v75, v[236:239]
	v_mfma_f32_4x4x1_16b_f32 v[240:243], v227, v6, v[240:243]
	v_mfma_f32_4x4x1_16b_f32 v[244:247], v227, v7, v[244:247]
	s_waitcnt lgkmcnt(0)
; #define LAS __attribute__((address_space(3)))
; __device__ __forceinline__ unsigned f2bf(float f) { unsigned u = __builtin_bit_cast(unsigned, f); return (u + 0x7fffu + ((u >> 16) & 1u)) >> 16; }
; __device__ __forceinline__ void s5_phase(LAS unsigned char* lds, const unsigned char* ws, const bf16_t* proj, const float* c_re, const float* c_im, const float* dskip, bf16_t* z,
;                                          int vcu, int G, int wave, int lane) {
;     ...
;             for (int k = 0; k < 32; ++k) {
;                 f32x2 xa = (f32x2){0.f, 0.f}, xb = (f32x2){0.f, 0.f};
; #pragma unroll
;                 for (int q = 0; q < 4; ++q) { const f32x4 u4 = *(const LAS f32x4*)(Uc + k * 16 + 4 * q);
;                     xa = __builtin_elementwise_fma((f32x2){u4[0], u4[0]}, (f32x2){bbre[4 * q], bbim[4 * q]}, xa);
;                     xb = __builtin_elementwise_fma((f32x2){u4[1], u4[1]}, (f32x2){bbre[4 * q + 1], bbim[4 * q + 1]}, xb);
;                     xa = __builtin_elementwise_fma((f32x2){u4[2], u4[2]}, (f32x2){bbre[4 * q + 2], bbim[4 * q + 2]}, xa);
;                     xb = __builtin_elementwise_fma((f32x2){u4[3], u4[3]}, (f32x2){bbre[4 * q + 3], bbim[4 * q + 3]}, xb); }
;                 const f32x2 xx = xa + xb;
;                 const float nr = are * hre - aim * him + xx[0], ni = are * him + aim * hre + xx[1]; hre = nr; him = ni;
;                 Hc[k * 136 + n] = (bf16_t)f2bf(hre); Hc[k * 136 + 64 + n] = (bf16_t)f2bf(him);
	v_mfma_f32_4x4x1_16b_f32 v[232:235], v228, v76, v[232:235]
	v_mfma_f32_4x4x1_16b_f32 v[236:239], v228, v77, v[236:239]
	v_mfma_f32_4x4x1_16b_f32 v[240:243], v229, v0, v[240:243]
	v_mfma_f32_4x4x1_16b_f32 v[244:247], v229, v1, v[244:247]
	v_mfma_f32_4x4x1_16b_f32 v[232:235], v230, v78, v[232:235]
	v_mfma_f32_4x4x1_16b_f32 v[236:239], v230, v79, v[236:239]
	v_mfma_f32_4x4x1_16b_f32 v[240:243], v231, v2, v[240:243]
	v_mfma_f32_4x4x1_16b_f32 v[244:247], v231, v3, v[244:247]
	s_nop 2
	v_add_f32_e32 v42, v240, v232
	v_add_f32_e32 v43, v244, v236
	v_pk_mul_f32 v[44:45], v[50:51], v[46:47]
	s_nop 0
	v_pk_fma_f32 v[44:45], v[60:61], v[134:135], v[44:45] neg_lo:[0,0,1] neg_hi:[0,0,1]
	s_nop 0
	v_pk_add_f32 v[86:87], v[44:45], v[42:43]
	v_pk_mul_f32 v[44:45], v[50:51], v[134:135]
	v_pk_fma_f32 v[44:45], v[60:61], v[46:47], v[44:45]
	v_pk_add_f32 v[46:47], v[44:45], v[42:43] op_sel:[0,1] op_sel_hi:[1,0]
	v_cvt_pk_bf16_f32 v41, v86, v46
	ds_write_b16 v88, v41 offset:2176
	ds_write_b16_d16_hi v88, v41 offset:2304
	v_add_f32_e32 v42, v241, v233
	v_add_f32_e32 v43, v245, v237
	v_pk_mul_f32 v[44:45], v[50:51], v[46:47]
	s_nop 0
	v_pk_fma_f32 v[44:45], v[60:61], v[86:87], v[44:45] neg_lo:[0,0,1] neg_hi:[0,0,1]
	s_nop 0
	v_pk_add_f32 v[134:135], v[44:45], v[42:43]
	v_pk_mul_f32 v[44:45], v[50:51], v[86:87]
	v_pk_fma_f32 v[44:45], v[60:61], v[46:47], v[44:45]
	v_pk_add_f32 v[46:47], v[44:45], v[42:43] op_sel:[0,1] op_sel_hi:[1,0]
	v_cvt_pk_bf16_f32 v41, v134, v46
	ds_write_b16 v88, v41 offset:2448
	ds_write_b16_d16_hi v88, v41 offset:2576
	v_add_f32_e32 v42, v242, v234
	v_add_f32_e32 v43, v246, v238
	v_pk_mul_f32 v[44:45], v[50:51], v[46:47]
	s_nop 0
	v_pk_fma_f32 v[44:45], v[60:61], v[134:135], v[44:45] neg_lo:[0,0,1] neg_hi:[0,0,1]
	s_nop 0
	v_pk_add_f32 v[86:87], v[44:45], v[42:43]
	v_pk_mul_f32 v[44:45], v[50:51], v[134:135]
	v_pk_fma_f32 v[44:45], v[60:61], v[46:47], v[44:45]
	v_pk_add_f32 v[46:47], v[44:45], v[42:43] op_sel:[0,1] op_sel_hi:[1,0]
	v_cvt_pk_bf16_f32 v41, v86, v46
	ds_write_b16 v88, v41 offset:2720
	ds_write_b16_d16_hi v88, v41 offset:2848
	v_add_f32_e32 v42, v243, v235
	v_add_f32_e32 v43, v247, v239
	v_pk_mul_f32 v[44:45], v[50:51], v[46:47]
	s_nop 0
	v_pk_fma_f32 v[44:45], v[60:61], v[86:87], v[44:45] neg_lo:[0,0,1] neg_hi:[0,0,1]
	s_nop 0
	v_pk_add_f32 v[134:135], v[44:45], v[42:43]
	v_pk_mul_f32 v[44:45], v[50:51], v[86:87]
	v_pk_fma_f32 v[44:45], v[60:61], v[46:47], v[44:45]
	v_pk_add_f32 v[46:47], v[44:45], v[42:43] op_sel:[0,1] op_sel_hi:[1,0]
	v_cvt_pk_bf16_f32 v41, v134, v46
	ds_write_b16 v88, v41 offset:2992
	ds_write_b16_d16_hi v88, v41 offset:3120
	ds_read_b128 v[216:219], v248 offset:768
	ds_read_b128 v[220:223], v248 offset:784
	ds_read_b128 v[224:227], v248 offset:800
	ds_read_b128 v[228:231], v248 offset:816
	s_waitcnt lgkmcnt(3)
	v_mfma_f32_4x4x1_16b_f32 v[232:235], v216, v64, 0
	v_mfma_f32_4x4x1_16b_f32 v[236:239], v216, v65, 0
	v_mfma_f32_4x4x1_16b_f32 v[240:243], v217, v12, 0
	v_mfma_f32_4x4x1_16b_f32 v[244:247], v217, v13, 0
	v_mfma_f32_4x4x1_16b_f32 v[232:235], v218, v66, v[232:235]
	v_mfma_f32_4x4x1_16b_f32 v[236:239], v218, v67, v[236:239]
	v_mfma_f32_4x4x1_16b_f32 v[240:243], v219, v14, v[240:243]
	v_mfma_f32_4x4x1_16b_f32 v[244:247], v219, v15, v[244:247]
	s_waitcnt lgkmcnt(2)
	v_mfma_f32_4x4x1_16b_f32 v[232:235], v220, v68, v[232:235]
	v_mfma_f32_4x4x1_16b_f32 v[236:239], v220, v69, v[236:239]
	v_mfma_f32_4x4x1_16b_f32 v[240:243], v221, v8, v[240:243]
	v_mfma_f32_4x4x1_16b_f32 v[244:247], v221, v9, v[244:247]
	v_mfma_f32_4x4x1_16b_f32 v[232:235], v222, v70, v[232:235]
	v_mfma_f32_4x4x1_16b_f32 v[236:239], v222, v71, v[236:239]
	v_mfma_f32_4x4x1_16b_f32 v[240:243], v223, v10, v[240:243]
	v_mfma_f32_4x4x1_16b_f32 v[244:247], v223, v11, v[244:247]
	s_waitcnt lgkmcnt(1)
	v_mfma_f32_4x4x1_16b_f32 v[232:235], v224, v72, v[232:235]
	v_mfma_f32_4x4x1_16b_f32 v[236:239], v224, v73, v[236:239]
	v_mfma_f32_4x4x1_16b_f32 v[240:243], v225, v4, v[240:243]
	v_mfma_f32_4x4x1_16b_f32 v[244:247], v225, v5, v[244:247]
	v_mfma_f32_4x4x1_16b_f32 v[232:235], v226, v74, v[232:235]
	v_mfma_f32_4x4x1_16b_f32 v[236:239], v226, v75, v[236:239]
	v_mfma_f32_4x4x1_16b_f32 v[240:243], v227, v6, v[240:243]
	v_mfma_f32_4x4x1_16b_f32 v[244:247], v227, v7, v[244:247]
	s_waitcnt lgkmcnt(0)
; #define LAS __attribute__((address_space(3)))
; __device__ __forceinline__ unsigned f2bf(float f) { unsigned u = __builtin_bit_cast(unsigned, f); return (u + 0x7fffu + ((u >> 16) & 1u)) >> 16; }
; __device__ __forceinline__ void s5_phase(LAS unsigned char* lds, const unsigned char* ws, const bf16_t* proj, const float* c_re, const float* c_im, const float* dskip, bf16_t* z,
;                                          int vcu, int G, int wave, int lane) {
;     ...
;             for (int k = 0; k < 32; ++k) {
;                 f32x2 xa = (f32x2){0.f, 0.f}, xb = (f32x2){0.f, 0.f};
; #pragma unroll
;                 for (int q = 0; q < 4; ++q) { const f32x4 u4 = *(const LAS f32x4*)(Uc + k * 16 + 4 * q);
;                     xa = __builtin_elementwise_fma((f32x2){u4[0], u4[0]}, (f32x2){bbre[4 * q], bbim[4 * q]}, xa);
;                     xb = __builtin_elementwise_fma((f32x2){u4[1], u4[1]}, (f32x2){bbre[4 * q + 1], bbim[4 * q + 1]}, xb);
;                     xa = __builtin_elementwise_fma((f32x2){u4[2], u4[2]}, (f32x2){bbre[4 * q + 2], bbim[4 * q + 2]}, xa);
;                     xb = __builtin_elementwise_fma((f32x2){u4[3], u4[3]}, (f32x2){bbre[4 * q + 3], bbim[4 * q + 3]}, xb); }
;                 const f32x2 xx = xa + xb;
;                 const float nr = are * hre - aim * him + xx[0], ni = are * him + aim * hre + xx[1]; hre = nr; him = ni;
;                 Hc[k * 136 + n] = (bf16_t)f2bf(hre); Hc[k * 136 + 64 + n] = (bf16_t)f2bf(him);
	v_mfma_f32_4x4x1_16b_f32 v[232:235], v228, v76, v[232:235]
	v_mfma_f32_4x4x1_16b_f32 v[236:239], v228, v77, v[236:239]
	v_mfma_f32_4x4x1_16b_f32 v[240:243], v229, v0, v[240:243]
	v_mfma_f32_4x4x1_16b_f32 v[244:247], v229, v1, v[244:247]
	v_mfma_f32_4x4x1_16b_f32 v[232:235], v230, v78, v[232:235]
	v_mfma_f32_4x4x1_16b_f32 v[236:239], v230, v79, v[236:239]
	v_mfma_f32_4x4x1_16b_f32 v[240:243], v231, v2, v[240:243]
	v_mfma_f32_4x4x1_16b_f32 v[244:247], v231, v3, v[244:247]
	s_nop 2
	v_add_f32_e32 v42, v240, v232
	v_add_f32_e32 v43, v244, v236
	v_pk_mul_f32 v[44:45], v[50:51], v[46:47]
	s_nop 0
	v_pk_fma_f32 v[44:45], v[60:61], v[134:135], v[44:45] neg_lo:[0,0,1] neg_hi:[0,0,1]
	s_nop 0
	v_pk_add_f32 v[86:87], v[44:45], v[42:43]
	v_pk_mul_f32 v[44:45], v[50:51], v[134:135]
	v_pk_fma_f32 v[44:45], v[60:61], v[46:47], v[44:45]
	v_pk_add_f32 v[46:47], v[44:45], v[42:43] op_sel:[0,1] op_sel_hi:[1,0]
	v_cvt_pk_bf16_f32 v41, v86, v46
	ds_write_b16 v88, v41 offset:3264
	ds_write_b16_d16_hi v88, v41 offset:3392
	v_add_f32_e32 v42, v241, v233
	v_add_f32_e32 v43, v245, v237
	v_pk_mul_f32 v[44:45], v[50:51], v[46:47]
	s_nop 0
	v_pk_fma_f32 v[44:45], v[60:61], v[86:87], v[44:45] neg_lo:[0,0,1] neg_hi:[0,0,1]
	s_nop 0
	v_pk_add_f32 v[134:135], v[44:45], v[42:43]
	v_pk_mul_f32 v[44:45], v[50:51], v[86:87]
	v_pk_fma_f32 v[44:45], v[60:61], v[46:47], v[44:45]
	v_pk_add_f32 v[46:47], v[44:45], v[42:43] op_sel:[0,1] op_sel_hi:[1,0]
	v_cvt_pk_bf16_f32 v41, v134, v46
	ds_write_b16 v88, v41 offset:3536
	ds_write_b16_d16_hi v88, v41 offset:3664
	v_add_f32_e32 v42, v242, v234
	v_add_f32_e32 v43, v246, v238
	v_pk_mul_f32 v[44:45], v[50:51], v[46:47]
	s_nop 0
	v_pk_fma_f32 v[44:45], v[60:61], v[134:135], v[44:45] neg_lo:[0,0,1] neg_hi:[0,0,1]
	s_nop 0
	v_pk_add_f32 v[86:87], v[44:45], v[42:43]
	v_pk_mul_f32 v[44:45], v[50:51], v[134:135]
	v_pk_fma_f32 v[44:45], v[60:61], v[46:47], v[44:45]
	v_pk_add_f32 v[46:47], v[44:45], v[42:43] op_sel:[0,1] op_sel_hi:[1,0]
	v_cvt_pk_bf16_f32 v41, v86, v46
	ds_write_b16 v88, v41 offset:3808
	ds_write_b16_d16_hi v88, v41 offset:3936
	v_add_f32_e32 v42, v243, v235
	v_add_f32_e32 v43, v247, v239
	v_pk_mul_f32 v[44:45], v[50:51], v[46:47]
	s_nop 0
	v_pk_fma_f32 v[44:45], v[60:61], v[86:87], v[44:45] neg_lo:[0,0,1] neg_hi:[0,0,1]
	s_nop 0
	v_pk_add_f32 v[134:135], v[44:45], v[42:43]
	v_pk_mul_f32 v[44:45], v[50:51], v[86:87]
	v_pk_fma_f32 v[44:45], v[60:61], v[46:47], v[44:45]
	v_pk_add_f32 v[46:47], v[44:45], v[42:43] op_sel:[0,1] op_sel_hi:[1,0]
	v_cvt_pk_bf16_f32 v41, v134, v46
	ds_write_b16 v88, v41 offset:4080
	ds_write_b16_d16_hi v88, v41 offset:4208
	ds_read_b128 v[216:219], v248 offset:1024
	ds_read_b128 v[220:223], v248 offset:1040
	ds_read_b128 v[224:227], v248 offset:1056
	ds_read_b128 v[228:231], v248 offset:1072
	s_waitcnt lgkmcnt(3)
	v_mfma_f32_4x4x1_16b_f32 v[232:235], v216, v64, 0
	v_mfma_f32_4x4x1_16b_f32 v[236:239], v216, v65, 0
	v_mfma_f32_4x4x1_16b_f32 v[240:243], v217, v12, 0
	v_mfma_f32_4x4x1_16b_f32 v[244:247], v217, v13, 0
	v_mfma_f32_4x4x1_16b_f32 v[232:235], v218, v66, v[232:235]
	v_mfma_f32_4x4x1_16b_f32 v[236:239], v218, v67, v[236:239]
	v_mfma_f32_4x4x1_16b_f32 v[240:243], v219, v14, v[240:243]
	v_mfma_f32_4x4x1_16b_f32 v[244:247], v219, v15, v[244:247]
	s_waitcnt lgkmcnt(2)
	v_mfma_f32_4x4x1_16b_f32 v[232:235], v220, v68, v[232:235]
	v_mfma_f32_4x4x1_16b_f32 v[236:239], v220, v69, v[236:239]
	v_mfma_f32_4x4x1_16b_f32 v[240:243], v221, v8, v[240:243]
	v_mfma_f32_4x4x1_16b_f32 v[244:247], v221, v9, v[244:247]
	v_mfma_f32_4x4x1_16b_f32 v[232:235], v222, v70, v[232:235]
	v_mfma_f32_4x4x1_16b_f32 v[236:239], v222, v71, v[236:239]
	v_mfma_f32_4x4x1_16b_f32 v[240:243], v223, v10, v[240:243]
	v_mfma_f32_4x4x1_16b_f32 v[244:247], v223, v11, v[244:247]
	s_waitcnt lgkmcnt(1)
	v_mfma_f32_4x4x1_16b_f32 v[232:235], v224, v72, v[232:235]
	v_mfma_f32_4x4x1_16b_f32 v[236:239], v224, v73, v[236:239]
	v_mfma_f32_4x4x1_16b_f32 v[240:243], v225, v4, v[240:243]
	v_mfma_f32_4x4x1_16b_f32 v[244:247], v225, v5, v[244:247]
	v_mfma_f32_4x4x1_16b_f32 v[232:235], v226, v74, v[232:235]
	v_mfma_f32_4x4x1_16b_f32 v[236:239], v226, v75, v[236:239]
	v_mfma_f32_4x4x1_16b_f32 v[240:243], v227, v6, v[240:243]
	v_mfma_f32_4x4x1_16b_f32 v[244:247], v227, v7, v[244:247]
	s_waitcnt lgkmcnt(0)
; #define LAS __attribute__((address_space(3)))
; __device__ __forceinline__ unsigned f2bf(float f) { unsigned u = __builtin_bit_cast(unsigned, f); return (u + 0x7fffu + ((u >> 16) & 1u)) >> 16; }
; __device__ __forceinline__ void s5_phase(LAS unsigned char* lds, const unsigned char* ws, const bf16_t* proj, const float* c_re, const float* c_im, const float* dskip, bf16_t* z,
;                                          int vcu, int G, int wave, int lane) {
;     ...
;             for (int k = 0; k < 32; ++k) {
;                 f32x2 xa = (f32x2){0.f, 0.f}, xb = (f32x2){0.f, 0.f};
; #pragma unroll
;                 for (int q = 0; q < 4; ++q) { const f32x4 u4 = *(const LAS f32x4*)(Uc + k * 16 + 4 * q);
;                     xa = __builtin_elementwise_fma((f32x2){u4[0], u4[0]}, (f32x2){bbre[4 * q], bbim[4 * q]}, xa);
;                     xb = __builtin_elementwise_fma((f32x2){u4[1], u4[1]}, (f32x2){bbre[4 * q + 1], bbim[4 * q + 1]}, xb);
;                     xa = __builtin_elementwise_fma((f32x2){u4[2], u4[2]}, (f32x2){bbre[4 * q + 2], bbim[4 * q + 2]}, xa);
;                     xb = __builtin_elementwise_fma((f32x2){u4[3], u4[3]}, (f32x2){bbre[4 * q + 3], bbim[4 * q + 3]}, xb); }
;                 const f32x2 xx = xa + xb;
;                 const float nr = are * hre - aim * him + xx[0], ni = are * him + aim * hre + xx[1]; hre = nr; him = ni;
;                 Hc[k * 136 + n] = (bf16_t)f2bf(hre); Hc[k * 136 + 64 + n] = (bf16_t)f2bf(him);
	v_mfma_f32_4x4x1_16b_f32 v[232:235], v228, v76, v[232:235]
	v_mfma_f32_4x4x1_16b_f32 v[236:239], v228, v77, v[236:239]
	v_mfma_f32_4x4x1_16b_f32 v[240:243], v229, v0, v[240:243]
	v_mfma_f32_4x4x1_16b_f32 v[244:247], v229, v1, v[244:247]
	v_mfma_f32_4x4x1_16b_f32 v[232:235], v230, v78, v[232:235]
	v_mfma_f32_4x4x1_16b_f32 v[236:239], v230, v79, v[236:239]
	v_mfma_f32_4x4x1_16b_f32 v[240:243], v231, v2, v[240:243]
	v_mfma_f32_4x4x1_16b_f32 v[244:247], v231, v3, v[244:247]
	s_nop 2
	v_add_f32_e32 v42, v240, v232
	v_add_f32_e32 v43, v244, v236
	v_pk_mul_f32 v[44:45], v[50:51], v[46:47]
	s_nop 0
	v_pk_fma_f32 v[44:45], v[60:61], v[134:135], v[44:45] neg_lo:[0,0,1] neg_hi:[0,0,1]
	s_nop 0
	v_pk_add_f32 v[86:87], v[44:45], v[42:43]
	v_pk_mul_f32 v[44:45], v[50:51], v[134:135]
	v_pk_fma_f32 v[44:45], v[60:61], v[46:47], v[44:45]
	v_pk_add_f32 v[46:47], v[44:45], v[42:43] op_sel:[0,1] op_sel_hi:[1,0]
	v_cvt_pk_bf16_f32 v41, v86, v46
	ds_write_b16 v88, v41 offset:4352
	ds_write_b16_d16_hi v88, v41 offset:4480
	v_add_f32_e32 v42, v241, v233
	v_add_f32_e32 v43, v245, v237
	v_pk_mul_f32 v[44:45], v[50:51], v[46:47]
	s_nop 0
	v_pk_fma_f32 v[44:45], v[60:61], v[86:87], v[44:45] neg_lo:[0,0,1] neg_hi:[0,0,1]
	s_nop 0
	v_pk_add_f32 v[134:135], v[44:45], v[42:43]
	v_pk_mul_f32 v[44:45], v[50:51], v[86:87]
	v_pk_fma_f32 v[44:45], v[60:61], v[46:47], v[44:45]
	v_pk_add_f32 v[46:47], v[44:45], v[42:43] op_sel:[0,1] op_sel_hi:[1,0]
	v_cvt_pk_bf16_f32 v41, v134, v46
	ds_write_b16 v88, v41 offset:4624
	ds_write_b16_d16_hi v88, v41 offset:4752
	v_add_f32_e32 v42, v242, v234
	v_add_f32_e32 v43, v246, v238
	v_pk_mul_f32 v[44:45], v[50:51], v[46:47]
	s_nop 0
	v_pk_fma_f32 v[44:45], v[60:61], v[134:135], v[44:45] neg_lo:[0,0,1] neg_hi:[0,0,1]
	s_nop 0
	v_pk_add_f32 v[86:87], v[44:45], v[42:43]
	v_pk_mul_f32 v[44:45], v[50:51], v[134:135]
	v_pk_fma_f32 v[44:45], v[60:61], v[46:47], v[44:45]
	v_pk_add_f32 v[46:47], v[44:45], v[42:43] op_sel:[0,1] op_sel_hi:[1,0]
	v_cvt_pk_bf16_f32 v41, v86, v46
	ds_write_b16 v88, v41 offset:4896
	ds_write_b16_d16_hi v88, v41 offset:5024
	v_add_f32_e32 v42, v243, v235
	v_add_f32_e32 v43, v247, v239
	v_pk_mul_f32 v[44:45], v[50:51], v[46:47]
	s_nop 0
	v_pk_fma_f32 v[44:45], v[60:61], v[86:87], v[44:45] neg_lo:[0,0,1] neg_hi:[0,0,1]
	s_nop 0
	v_pk_add_f32 v[134:135], v[44:45], v[42:43]
	v_pk_mul_f32 v[44:45], v[50:51], v[86:87]
	v_pk_fma_f32 v[44:45], v[60:61], v[46:47], v[44:45]
	v_pk_add_f32 v[46:47], v[44:45], v[42:43] op_sel:[0,1] op_sel_hi:[1,0]
	v_cvt_pk_bf16_f32 v41, v134, v46
	ds_write_b16 v88, v41 offset:5168
	ds_write_b16_d16_hi v88, v41 offset:5296
	ds_read_b128 v[216:219], v248 offset:1280
	ds_read_b128 v[220:223], v248 offset:1296
	ds_read_b128 v[224:227], v248 offset:1312
	ds_read_b128 v[228:231], v248 offset:1328
	s_waitcnt lgkmcnt(3)
	v_mfma_f32_4x4x1_16b_f32 v[232:235], v216, v64, 0
	v_mfma_f32_4x4x1_16b_f32 v[236:239], v216, v65, 0
	v_mfma_f32_4x4x1_16b_f32 v[240:243], v217, v12, 0
	v_mfma_f32_4x4x1_16b_f32 v[244:247], v217, v13, 0
	v_mfma_f32_4x4x1_16b_f32 v[232:235], v218, v66, v[232:235]
	v_mfma_f32_4x4x1_16b_f32 v[236:239], v218, v67, v[236:239]
	v_mfma_f32_4x4x1_16b_f32 v[240:243], v219, v14, v[240:243]
	v_mfma_f32_4x4x1_16b_f32 v[244:247], v219, v15, v[244:247]
	s_waitcnt lgkmcnt(2)
	v_mfma_f32_4x4x1_16b_f32 v[232:235], v220, v68, v[232:235]
	v_mfma_f32_4x4x1_16b_f32 v[236:239], v220, v69, v[236:239]
	v_mfma_f32_4x4x1_16b_f32 v[240:243], v221, v8, v[240:243]
	v_mfma_f32_4x4x1_16b_f32 v[244:247], v221, v9, v[244:247]
	v_mfma_f32_4x4x1_16b_f32 v[232:235], v222, v70, v[232:235]
	v_mfma_f32_4x4x1_16b_f32 v[236:239], v222, v71, v[236:239]
	v_mfma_f32_4x4x1_16b_f32 v[240:243], v223, v10, v[240:243]
	v_mfma_f32_4x4x1_16b_f32 v[244:247], v223, v11, v[244:247]
	s_waitcnt lgkmcnt(1)
	v_mfma_f32_4x4x1_16b_f32 v[232:235], v224, v72, v[232:235]
	v_mfma_f32_4x4x1_16b_f32 v[236:239], v224, v73, v[236:239]
	v_mfma_f32_4x4x1_16b_f32 v[240:243], v225, v4, v[240:243]
	v_mfma_f32_4x4x1_16b_f32 v[244:247], v225, v5, v[244:247]
	v_mfma_f32_4x4x1_16b_f32 v[232:235], v226, v74, v[232:235]
	v_mfma_f32_4x4x1_16b_f32 v[236:239], v226, v75, v[236:239]
	v_mfma_f32_4x4x1_16b_f32 v[240:243], v227, v6, v[240:243]
	v_mfma_f32_4x4x1_16b_f32 v[244:247], v227, v7, v[244:247]
	s_waitcnt lgkmcnt(0)
; #define LAS __attribute__((address_space(3)))
; __device__ __forceinline__ unsigned f2bf(float f) { unsigned u = __builtin_bit_cast(unsigned, f); return (u + 0x7fffu + ((u >> 16) & 1u)) >> 16; }
; __device__ __forceinline__ void s5_phase(LAS unsigned char* lds, const unsigned char* ws, const bf16_t* proj, const float* c_re, const float* c_im, const float* dskip, bf16_t* z,
;                                          int vcu, int G, int wave, int lane) {
;     ...
;             for (int k = 0; k < 32; ++k) {
;                 f32x2 xa = (f32x2){0.f, 0.f}, xb = (f32x2){0.f, 0.f};
; #pragma unroll
;                 for (int q = 0; q < 4; ++q) { const f32x4 u4 = *(const LAS f32x4*)(Uc + k * 16 + 4 * q);
;                     xa = __builtin_elementwise_fma((f32x2){u4[0], u4[0]}, (f32x2){bbre[4 * q], bbim[4 * q]}, xa);
;                     xb = __builtin_elementwise_fma((f32x2){u4[1], u4[1]}, (f32x2){bbre[4 * q + 1], bbim[4 * q + 1]}, xb);
;                     xa = __builtin_elementwise_fma((f32x2){u4[2], u4[2]}, (f32x2){bbre[4 * q + 2], bbim[4 * q + 2]}, xa);
;                     xb = __builtin_elementwise_fma((f32x2){u4[3], u4[3]}, (f32x2){bbre[4 * q + 3], bbim[4 * q + 3]}, xb); }
;                 const f32x2 xx = xa + xb;
;                 const float nr = are * hre - aim * him + xx[0], ni = are * him + aim * hre + xx[1]; hre = nr; him = ni;
;                 Hc[k * 136 + n] = (bf16_t)f2bf(hre); Hc[k * 136 + 64 + n] = (bf16_t)f2bf(him);
	v_mfma_f32_4x4x1_16b_f32 v[232:235], v228, v76, v[232:235]
	v_mfma_f32_4x4x1_16b_f32 v[236:239], v228, v77, v[236:239]
	v_mfma_f32_4x4x1_16b_f32 v[240:243], v229, v0, v[240:243]
	v_mfma_f32_4x4x1_16b_f32 v[244:247], v229, v1, v[244:247]
	v_mfma_f32_4x4x1_16b_f32 v[232:235], v230, v78, v[232:235]
	v_mfma_f32_4x4x1_16b_f32 v[236:239], v230, v79, v[236:239]
	v_mfma_f32_4x4x1_16b_f32 v[240:243], v231, v2, v[240:243]
	v_mfma_f32_4x4x1_16b_f32 v[244:247], v231, v3, v[244:247]
	s_nop 2
	v_add_f32_e32 v42, v240, v232
	v_add_f32_e32 v43, v244, v236
	v_pk_mul_f32 v[44:45], v[50:51], v[46:47]
	s_nop 0
	v_pk_fma_f32 v[44:45], v[60:61], v[134:135], v[44:45] neg_lo:[0,0,1] neg_hi:[0,0,1]
	s_nop 0
	v_pk_add_f32 v[86:87], v[44:45], v[42:43]
	v_pk_mul_f32 v[44:45], v[50:51], v[134:135]
	v_pk_fma_f32 v[44:45], v[60:61], v[46:47], v[44:45]
	v_pk_add_f32 v[46:47], v[44:45], v[42:43] op_sel:[0,1] op_sel_hi:[1,0]
	v_cvt_pk_bf16_f32 v41, v86, v46
	ds_write_b16 v88, v41 offset:5440
	ds_write_b16_d16_hi v88, v41 offset:5568
	v_add_f32_e32 v42, v241, v233
	v_add_f32_e32 v43, v245, v237
	v_pk_mul_f32 v[44:45], v[50:51], v[46:47]
	s_nop 0
	v_pk_fma_f32 v[44:45], v[60:61], v[86:87], v[44:45] neg_lo:[0,0,1] neg_hi:[0,0,1]
	s_nop 0
	v_pk_add_f32 v[134:135], v[44:45], v[42:43]
	v_pk_mul_f32 v[44:45], v[50:51], v[86:87]
	v_pk_fma_f32 v[44:45], v[60:61], v[46:47], v[44:45]
	v_pk_add_f32 v[46:47], v[44:45], v[42:43] op_sel:[0,1] op_sel_hi:[1,0]
	v_cvt_pk_bf16_f32 v41, v134, v46
	ds_write_b16 v88, v41 offset:5712
	ds_write_b16_d16_hi v88, v41 offset:5840
	v_add_f32_e32 v42, v242, v234
	v_add_f32_e32 v43, v246, v238
	v_pk_mul_f32 v[44:45], v[50:51], v[46:47]
	s_nop 0
	v_pk_fma_f32 v[44:45], v[60:61], v[134:135], v[44:45] neg_lo:[0,0,1] neg_hi:[0,0,1]
	s_nop 0
	v_pk_add_f32 v[86:87], v[44:45], v[42:43]
	v_pk_mul_f32 v[44:45], v[50:51], v[134:135]
	v_pk_fma_f32 v[44:45], v[60:61], v[46:47], v[44:45]
	v_pk_add_f32 v[46:47], v[44:45], v[42:43] op_sel:[0,1] op_sel_hi:[1,0]
	v_cvt_pk_bf16_f32 v41, v86, v46
	ds_write_b16 v88, v41 offset:5984
	ds_write_b16_d16_hi v88, v41 offset:6112
	v_add_f32_e32 v42, v243, v235
	v_add_f32_e32 v43, v247, v239
	v_pk_mul_f32 v[44:45], v[50:51], v[46:47]
	s_nop 0
	v_pk_fma_f32 v[44:45], v[60:61], v[86:87], v[44:45] neg_lo:[0,0,1] neg_hi:[0,0,1]
	s_nop 0
	v_pk_add_f32 v[134:135], v[44:45], v[42:43]
	v_pk_mul_f32 v[44:45], v[50:51], v[86:87]
	v_pk_fma_f32 v[44:45], v[60:61], v[46:47], v[44:45]
	v_pk_add_f32 v[46:47], v[44:45], v[42:43] op_sel:[0,1] op_sel_hi:[1,0]
	v_cvt_pk_bf16_f32 v41, v134, v46
	ds_write_b16 v88, v41 offset:6256
	ds_write_b16_d16_hi v88, v41 offset:6384
	ds_read_b128 v[216:219], v248 offset:1536
	ds_read_b128 v[220:223], v248 offset:1552
	ds_read_b128 v[224:227], v248 offset:1568
	ds_read_b128 v[228:231], v248 offset:1584
	s_waitcnt lgkmcnt(3)
	v_mfma_f32_4x4x1_16b_f32 v[232:235], v216, v64, 0
	v_mfma_f32_4x4x1_16b_f32 v[236:239], v216, v65, 0
	v_mfma_f32_4x4x1_16b_f32 v[240:243], v217, v12, 0
	v_mfma_f32_4x4x1_16b_f32 v[244:247], v217, v13, 0
	v_mfma_f32_4x4x1_16b_f32 v[232:235], v218, v66, v[232:235]
	v_mfma_f32_4x4x1_16b_f32 v[236:239], v218, v67, v[236:239]
	v_mfma_f32_4x4x1_16b_f32 v[240:243], v219, v14, v[240:243]
	v_mfma_f32_4x4x1_16b_f32 v[244:247], v219, v15, v[244:247]
	s_waitcnt lgkmcnt(2)
	v_mfma_f32_4x4x1_16b_f32 v[232:235], v220, v68, v[232:235]
	v_mfma_f32_4x4x1_16b_f32 v[236:239], v220, v69, v[236:239]
	v_mfma_f32_4x4x1_16b_f32 v[240:243], v221, v8, v[240:243]
	v_mfma_f32_4x4x1_16b_f32 v[244:247], v221, v9, v[244:247]
	v_mfma_f32_4x4x1_16b_f32 v[232:235], v222, v70, v[232:235]
	v_mfma_f32_4x4x1_16b_f32 v[236:239], v222, v71, v[236:239]
	v_mfma_f32_4x4x1_16b_f32 v[240:243], v223, v10, v[240:243]
	v_mfma_f32_4x4x1_16b_f32 v[244:247], v223, v11, v[244:247]
	s_waitcnt lgkmcnt(1)
	v_mfma_f32_4x4x1_16b_f32 v[232:235], v224, v72, v[232:235]
	v_mfma_f32_4x4x1_16b_f32 v[236:239], v224, v73, v[236:239]
	v_mfma_f32_4x4x1_16b_f32 v[240:243], v225, v4, v[240:243]
	v_mfma_f32_4x4x1_16b_f32 v[244:247], v225, v5, v[244:247]
	v_mfma_f32_4x4x1_16b_f32 v[232:235], v226, v74, v[232:235]
	v_mfma_f32_4x4x1_16b_f32 v[236:239], v226, v75, v[236:239]
	v_mfma_f32_4x4x1_16b_f32 v[240:243], v227, v6, v[240:243]
	v_mfma_f32_4x4x1_16b_f32 v[244:247], v227, v7, v[244:247]
	s_waitcnt lgkmcnt(0)
; #define LAS __attribute__((address_space(3)))
; __device__ __forceinline__ unsigned f2bf(float f) { unsigned u = __builtin_bit_cast(unsigned, f); return (u + 0x7fffu + ((u >> 16) & 1u)) >> 16; }
; __device__ __forceinline__ void s5_phase(LAS unsigned char* lds, const unsigned char* ws, const bf16_t* proj, const float* c_re, const float* c_im, const float* dskip, bf16_t* z,
;                                          int vcu, int G, int wave, int lane) {
;     ...
;             for (int k = 0; k < 32; ++k) {
;                 f32x2 xa = (f32x2){0.f, 0.f}, xb = (f32x2){0.f, 0.f};
; #pragma unroll
;                 for (int q = 0; q < 4; ++q) { const f32x4 u4 = *(const LAS f32x4*)(Uc + k * 16 + 4 * q);
;                     xa = __builtin_elementwise_fma((f32x2){u4[0], u4[0]}, (f32x2){bbre[4 * q], bbim[4 * q]}, xa);
;                     xb = __builtin_elementwise_fma((f32x2){u4[1], u4[1]}, (f32x2){bbre[4 * q + 1], bbim[4 * q + 1]}, xb);
;                     xa = __builtin_elementwise_fma((f32x2){u4[2], u4[2]}, (f32x2){bbre[4 * q + 2], bbim[4 * q + 2]}, xa);
;                     xb = __builtin_elementwise_fma((f32x2){u4[3], u4[3]}, (f32x2){bbre[4 * q + 3], bbim[4 * q + 3]}, xb); }
;                 const f32x2 xx = xa + xb;
;                 const float nr = are * hre - aim * him + xx[0], ni = are * him + aim * hre + xx[1]; hre = nr; him = ni;
;                 Hc[k * 136 + n] = (bf16_t)f2bf(hre); Hc[k * 136 + 64 + n] = (bf16_t)f2bf(him);
;             }
; #pragma unroll
;             for (int sb = 0; sb < 2; ++sb) {
;                 f32x4 y = (f32x4){0.f, 0.f, 0.f, 0.f};
; #pragma unroll
;                 for (int ks = 0; ks < 4; ++ks) { const bf16x8 hf = *(const LAS bf16x8*)(Hc + (16 * sb + fr) * 136 + 32 * ks + 8 * fq); y = __builtin_amdgcn_mfma_f32_16x16x32_bf16(hf, cf[ks], y, 0, 0, 0); }
	v_mfma_f32_4x4x1_16b_f32 v[232:235], v228, v76, v[232:235]
	v_mfma_f32_4x4x1_16b_f32 v[236:239], v228, v77, v[236:239]
	v_mfma_f32_4x4x1_16b_f32 v[240:243], v229, v0, v[240:243]
	v_mfma_f32_4x4x1_16b_f32 v[244:247], v229, v1, v[244:247]
	v_mfma_f32_4x4x1_16b_f32 v[232:235], v230, v78, v[232:235]
	v_mfma_f32_4x4x1_16b_f32 v[236:239], v230, v79, v[236:239]
	v_mfma_f32_4x4x1_16b_f32 v[240:243], v231, v2, v[240:243]
	v_mfma_f32_4x4x1_16b_f32 v[244:247], v231, v3, v[244:247]
	s_nop 2
	v_add_f32_e32 v42, v240, v232
	v_add_f32_e32 v43, v244, v236
	v_pk_mul_f32 v[44:45], v[50:51], v[46:47]
	s_nop 0
	v_pk_fma_f32 v[44:45], v[60:61], v[134:135], v[44:45] neg_lo:[0,0,1] neg_hi:[0,0,1]
	s_nop 0
	v_pk_add_f32 v[86:87], v[44:45], v[42:43]
	v_pk_mul_f32 v[44:45], v[50:51], v[134:135]
	v_pk_fma_f32 v[44:45], v[60:61], v[46:47], v[44:45]
	v_pk_add_f32 v[46:47], v[44:45], v[42:43] op_sel:[0,1] op_sel_hi:[1,0]
	v_cvt_pk_bf16_f32 v41, v86, v46
	ds_write_b16 v88, v41 offset:6528
	ds_write_b16_d16_hi v88, v41 offset:6656
	v_add_f32_e32 v42, v241, v233
	v_add_f32_e32 v43, v245, v237
	v_pk_mul_f32 v[44:45], v[50:51], v[46:47]
	s_nop 0
	v_pk_fma_f32 v[44:45], v[60:61], v[86:87], v[44:45] neg_lo:[0,0,1] neg_hi:[0,0,1]
	s_nop 0
	v_pk_add_f32 v[134:135], v[44:45], v[42:43]
	v_pk_mul_f32 v[44:45], v[50:51], v[86:87]
	v_pk_fma_f32 v[44:45], v[60:61], v[46:47], v[44:45]
	v_pk_add_f32 v[46:47], v[44:45], v[42:43] op_sel:[0,1] op_sel_hi:[1,0]
	v_cvt_pk_bf16_f32 v41, v134, v46
	ds_write_b16 v88, v41 offset:6800
	ds_write_b16_d16_hi v88, v41 offset:6928
	v_add_f32_e32 v42, v242, v234
	v_add_f32_e32 v43, v246, v238
	v_pk_mul_f32 v[44:45], v[50:51], v[46:47]
	s_nop 0
	v_pk_fma_f32 v[44:45], v[60:61], v[134:135], v[44:45] neg_lo:[0,0,1] neg_hi:[0,0,1]
	s_nop 0
	v_pk_add_f32 v[86:87], v[44:45], v[42:43]
	v_pk_mul_f32 v[44:45], v[50:51], v[134:135]
	v_pk_fma_f32 v[44:45], v[60:61], v[46:47], v[44:45]
	v_pk_add_f32 v[46:47], v[44:45], v[42:43] op_sel:[0,1] op_sel_hi:[1,0]
	v_cvt_pk_bf16_f32 v41, v86, v46
	ds_write_b16 v88, v41 offset:7072
	ds_write_b16_d16_hi v88, v41 offset:7200
	v_add_f32_e32 v42, v243, v235
	v_add_f32_e32 v43, v247, v239
	v_pk_mul_f32 v[44:45], v[50:51], v[46:47]
	s_nop 0
	v_pk_fma_f32 v[44:45], v[60:61], v[86:87], v[44:45] neg_lo:[0,0,1] neg_hi:[0,0,1]
	s_nop 0
	v_pk_add_f32 v[134:135], v[44:45], v[42:43]
	v_pk_mul_f32 v[44:45], v[50:51], v[86:87]
	v_pk_fma_f32 v[44:45], v[60:61], v[46:47], v[44:45]
	v_pk_add_f32 v[46:47], v[44:45], v[42:43] op_sel:[0,1] op_sel_hi:[1,0]
	v_cvt_pk_bf16_f32 v41, v134, v46
	ds_write_b16 v88, v41 offset:7344
	ds_write_b16_d16_hi v88, v41 offset:7472
	ds_read_b128 v[216:219], v248 offset:1792
	ds_read_b128 v[220:223], v248 offset:1808
	ds_read_b128 v[224:227], v248 offset:1824
	ds_read_b128 v[228:231], v248 offset:1840
	s_waitcnt lgkmcnt(3)
	v_mfma_f32_4x4x1_16b_f32 v[232:235], v216, v64, 0
	v_mfma_f32_4x4x1_16b_f32 v[236:239], v216, v65, 0
	v_mfma_f32_4x4x1_16b_f32 v[240:243], v217, v12, 0
	v_mfma_f32_4x4x1_16b_f32 v[244:247], v217, v13, 0
	v_mfma_f32_4x4x1_16b_f32 v[232:235], v218, v66, v[232:235]
	v_mfma_f32_4x4x1_16b_f32 v[236:239], v218, v67, v[236:239]
	v_mfma_f32_4x4x1_16b_f32 v[240:243], v219, v14, v[240:243]
	v_mfma_f32_4x4x1_16b_f32 v[244:247], v219, v15, v[244:247]
	s_waitcnt lgkmcnt(2)
	v_mfma_f32_4x4x1_16b_f32 v[232:235], v220, v68, v[232:235]
	v_mfma_f32_4x4x1_16b_f32 v[236:239], v220, v69, v[236:239]
	v_mfma_f32_4x4x1_16b_f32 v[240:243], v221, v8, v[240:243]
	v_mfma_f32_4x4x1_16b_f32 v[244:247], v221, v9, v[244:247]
	v_mfma_f32_4x4x1_16b_f32 v[232:235], v222, v70, v[232:235]
	v_mfma_f32_4x4x1_16b_f32 v[236:239], v222, v71, v[236:239]
	v_mfma_f32_4x4x1_16b_f32 v[240:243], v223, v10, v[240:243]
	v_mfma_f32_4x4x1_16b_f32 v[244:247], v223, v11, v[244:247]
	s_waitcnt lgkmcnt(1)
	v_mfma_f32_4x4x1_16b_f32 v[232:235], v224, v72, v[232:235]
	v_mfma_f32_4x4x1_16b_f32 v[236:239], v224, v73, v[236:239]
	v_mfma_f32_4x4x1_16b_f32 v[240:243], v225, v4, v[240:243]
	v_mfma_f32_4x4x1_16b_f32 v[244:247], v225, v5, v[244:247]
	v_mfma_f32_4x4x1_16b_f32 v[232:235], v226, v74, v[232:235]
	v_mfma_f32_4x4x1_16b_f32 v[236:239], v226, v75, v[236:239]
	v_mfma_f32_4x4x1_16b_f32 v[240:243], v227, v6, v[240:243]
	v_mfma_f32_4x4x1_16b_f32 v[244:247], v227, v7, v[244:247]
	s_waitcnt lgkmcnt(0)
	v_mfma_f32_4x4x1_16b_f32 v[232:235], v228, v76, v[232:235]
	v_mfma_f32_4x4x1_16b_f32 v[236:239], v228, v77, v[236:239]
	v_mfma_f32_4x4x1_16b_f32 v[240:243], v229, v0, v[240:243]
	v_mfma_f32_4x4x1_16b_f32 v[244:247], v229, v1, v[244:247]
	v_mfma_f32_4x4x1_16b_f32 v[232:235], v230, v78, v[232:235]
	v_mfma_f32_4x4x1_16b_f32 v[236:239], v230, v79, v[236:239]
	v_mfma_f32_4x4x1_16b_f32 v[240:243], v231, v2, v[240:243]
	v_mfma_f32_4x4x1_16b_f32 v[244:247], v231, v3, v[244:247]
	s_nop 2
	v_add_f32_e32 v42, v240, v232
	v_add_f32_e32 v43, v244, v236
	v_pk_mul_f32 v[44:45], v[50:51], v[46:47]
	s_nop 0
	v_pk_fma_f32 v[44:45], v[60:61], v[134:135], v[44:45] neg_lo:[0,0,1] neg_hi:[0,0,1]
	s_nop 0
	v_pk_add_f32 v[86:87], v[44:45], v[42:43]
	v_pk_mul_f32 v[44:45], v[50:51], v[134:135]
	v_pk_fma_f32 v[44:45], v[60:61], v[46:47], v[44:45]
	v_pk_add_f32 v[46:47], v[44:45], v[42:43] op_sel:[0,1] op_sel_hi:[1,0]
	v_cvt_pk_bf16_f32 v41, v86, v46
	ds_write_b16 v88, v41 offset:7616
	ds_write_b16_d16_hi v88, v41 offset:7744
	v_add_f32_e32 v42, v241, v233
	v_add_f32_e32 v43, v245, v237
	v_pk_mul_f32 v[44:45], v[50:51], v[46:47]
	s_nop 0
	v_pk_fma_f32 v[44:45], v[60:61], v[86:87], v[44:45] neg_lo:[0,0,1] neg_hi:[0,0,1]
	s_nop 0
	v_pk_add_f32 v[134:135], v[44:45], v[42:43]
	v_pk_mul_f32 v[44:45], v[50:51], v[86:87]
	v_pk_fma_f32 v[44:45], v[60:61], v[46:47], v[44:45]
	v_pk_add_f32 v[46:47], v[44:45], v[42:43] op_sel:[0,1] op_sel_hi:[1,0]
	v_cvt_pk_bf16_f32 v41, v134, v46
	ds_write_b16 v88, v41 offset:7888
	ds_write_b16_d16_hi v88, v41 offset:8016
	v_add_f32_e32 v42, v242, v234
	v_add_f32_e32 v43, v246, v238
	v_pk_mul_f32 v[44:45], v[50:51], v[46:47]
	s_nop 0
	v_pk_fma_f32 v[44:45], v[60:61], v[134:135], v[44:45] neg_lo:[0,0,1] neg_hi:[0,0,1]
	s_nop 0
	v_pk_add_f32 v[86:87], v[44:45], v[42:43]
	v_pk_mul_f32 v[44:45], v[50:51], v[134:135]
	v_pk_fma_f32 v[44:45], v[60:61], v[46:47], v[44:45]
	v_pk_add_f32 v[46:47], v[44:45], v[42:43] op_sel:[0,1] op_sel_hi:[1,0]
	v_cvt_pk_bf16_f32 v41, v86, v46
	ds_write_b16 v88, v41 offset:8160
	ds_write_b16_d16_hi v88, v41 offset:8288
	v_add_f32_e32 v40, v243, v235
	v_add_f32_e32 v41, v247, v239
	v_pk_mul_f32 v[42:43], v[80:81], v[46:47] op_sel_hi:[1,0]
	v_lshl_add_u64 v[130:131], v[82:83], 0, s[26:27]
	v_pk_fma_f32 v[44:45], v[60:61], v[86:87], v[42:43] neg_lo:[0,0,1] neg_hi:[0,0,1]
	v_pk_fma_f32 v[42:43], v[60:61], v[86:87], v[42:43] op_sel_hi:[1,0,1]
	s_nop 0
	v_mov_b32_e32 v45, v43
	v_pk_add_f32 v[86:87], v[44:45], v[40:41]
	s_nop 0
	v_cvt_pk_bf16_f32 v40, v86, v87
	ds_write_b16 v88, v40 offset:8432
	ds_write_b16_d16_hi v88, v40 offset:8560
	ds_read_b128 v[40:43], v102
	ds_read_b128 v[44:47], v102 offset:64
	s_waitcnt lgkmcnt(1)
; #define LAS __attribute__((address_space(3)))
; __device__ __forceinline__ unsigned f2bf(float f) { unsigned u = __builtin_bit_cast(unsigned, f); return (u + 0x7fffu + ((u >> 16) & 1u)) >> 16; }
; __device__ __forceinline__ float gelu_tanh_f(float y) { return y * fast_sigmoid(1.5957691216057308f * (y + 0.044715f * y * y * y)); }
; __device__ __forceinline__ void s5_phase(LAS unsigned char* lds, const unsigned char* ws, const bf16_t* proj, const float* c_re, const float* c_im, const float* dskip, bf16_t* z,
;                                          int vcu, int G, int wave, int lane) {
;     ...
; #pragma unroll
;             for (int sb = 0; sb < 2; ++sb) {
;                 f32x4 y = (f32x4){0.f, 0.f, 0.f, 0.f};
; #pragma unroll
;                 for (int ks = 0; ks < 4; ++ks) { const bf16x8 hf = *(const LAS bf16x8*)(Hc + (16 * sb + fr) * 136 + 32 * ks + 8 * fq); y = __builtin_amdgcn_mfma_f32_16x16x32_bf16(hf, cf[ks], y, 0, 0, 0); }
; #pragma unroll
;                 for (int i = 0; i < 4; ++i) { const size_t row = row0 + 16 * sb + 4 * fq + i;
;                     const float yy = y[i] + dsk * bf2f(uu[sb][i]);
;                     z[row * 1024 + g * 16 + fr] = (bf16_t)f2bf(gelu_tanh_f(yy)); }
;             }
;             ua = ua_n; ub = ub_n;
; #pragma unroll
;             for (int sb = 0; sb < 2; ++sb)
; #pragma unroll
;                 for (int i = 0; i < 4; ++i) uu[sb][i] = uu_n[sb][i];
	v_mfma_f32_16x16x32_bf16 v[40:43], v[40:43], v[16:19], 0
	ds_read_b128 v[122:125], v102 offset:128
	ds_read_b128 v[126:129], v102 offset:4544
	s_waitcnt lgkmcnt(2)
	v_mfma_f32_16x16x32_bf16 v[40:43], v[44:47], v[20:23], v[40:43]
	ds_read_b128 v[44:47], v102 offset:192
	s_waitcnt lgkmcnt(2)
	v_mfma_f32_16x16x32_bf16 v[40:43], v[122:125], v[24:27], v[40:43]
	ds_read_b128 v[122:125], v102 offset:4480
	s_waitcnt lgkmcnt(1)
	v_mfma_f32_16x16x32_bf16 v[40:43], v[44:47], v[28:31], v[40:43]
	v_lshlrev_b32_e32 v44, 16, v120
	s_nop 6
	v_fma_f32 v40, v104, v44, v40
	v_mul_f32_e32 v44, 0x3d372713, v40
	v_mul_f32_e32 v44, v40, v44
	v_fma_f32 v44, v40, v44, v40
	v_mul_f32_e32 v44, 0x3fcc422a, v44
	v_mul_f32_e32 v44, 0xbfb8aa3b, v44
	v_exp_f32_e32 v44, v44
	s_nop 0
	v_add_f32_e32 v44, 1.0, v44
	v_rcp_f32_e32 v44, v44
	s_nop 0
	v_mul_f32_e32 v40, v40, v44
	v_bfe_u32 v44, v40, 16, 1
	v_add3_u32 v46, v40, v44, s29
	v_lshlrev_b32_e32 v40, 16, v119
	v_fma_f32 v47, v104, v40, v41
	v_mul_f32_e32 v40, 0x3d372713, v47
	v_mul_f32_e32 v40, v47, v40
	v_fma_f32 v40, v47, v40, v47
	v_mul_f32_e32 v40, 0x3fcc422a, v40
	v_mul_f32_e32 v40, 0xbfb8aa3b, v40
	v_lshl_add_u64 v[44:45], v[84:85], 0, s[26:27]
	v_exp_f32_e32 v119, v40
	v_add_co_u32_e64 v40, s[0:1], s31, v44
	s_add_u32 s26, s26, 0x10000
	s_nop 0
	v_addc_co_u32_e64 v41, s[0:1], 0, v45, s[0:1]
	v_add_co_u32_e64 v132, s[0:1], s33, v44
	v_add_f32_e32 v119, 1.0, v119
	s_nop 0
	v_addc_co_u32_e64 v133, s[0:1], 0, v45, s[0:1]
	v_rcp_f32_e32 v119, v119
	global_store_short_d16_hi v[132:133], v46, off offset:-4096
	v_lshlrev_b32_e32 v46, 16, v118
	v_fma_f32 v42, v104, v46, v42
	v_mul_f32_e32 v46, 0x3d372713, v42
	v_mul_f32_e32 v46, v42, v46
	v_mul_f32_e32 v44, v47, v119
	v_fma_f32 v46, v42, v46, v42
	v_bfe_u32 v45, v44, 16, 1
	v_mul_f32_e32 v46, 0x3fcc422a, v46
	v_mul_f32_e32 v46, 0xbfb8aa3b, v46
	v_add3_u32 v44, v44, v45, s29
	v_exp_f32_e32 v118, v46
	global_store_short_d16_hi v[40:41], v44, off offset:2048
	ds_read_b128 v[44:47], v102 offset:4352
	v_lshlrev_b32_e32 v41, 16, v109
	v_add_f32_e32 v40, 1.0, v118
	ds_read_b128 v[118:121], v102 offset:4416
	s_waitcnt lgkmcnt(1)
	v_mfma_f32_16x16x32_bf16 v[44:47], v[44:47], v[16:19], 0
	v_fmac_f32_e32 v43, v104, v41
	v_mul_f32_e32 v41, 0x3d372713, v43
	v_mul_f32_e32 v41, v43, v41
	s_waitcnt lgkmcnt(0)
	v_mfma_f32_16x16x32_bf16 v[44:47], v[118:121], v[20:23], v[44:47]
	v_fma_f32 v41, v43, v41, v43
	v_mul_f32_e32 v41, 0x3fcc422a, v41
	v_mul_f32_e32 v41, 0xbfb8aa3b, v41
	v_mfma_f32_16x16x32_bf16 v[44:47], v[122:125], v[24:27], v[44:47]
	v_exp_f32_e32 v41, v41
	v_rcp_f32_e32 v40, v40
	s_addc_u32 s27, s27, 0
	v_mfma_f32_16x16x32_bf16 v[44:47], v[126:129], v[28:31], v[44:47]
	v_add_f32_e32 v41, 1.0, v41
	v_rcp_f32_e32 v41, v41
	v_mul_f32_e32 v40, v42, v40
	v_bfe_u32 v42, v40, 16, 1
	v_add3_u32 v40, v40, v42, s29
	s_nop 2
	v_fma_f32 v44, v104, v108, v44
	v_mul_f32_e32 v108, 0x3d372713, v44
	v_mul_f32_e32 v108, v44, v108
	v_fma_f32 v108, v44, v108, v44
	v_mul_f32_e32 v108, 0x3fcc422a, v108
	v_mul_f32_e32 v108, 0xbfb8aa3b, v108
	v_exp_f32_e32 v108, v108
	global_store_short_d16_hi v[132:133], v40, off
	v_mul_f32_e32 v40, v43, v41
	v_bfe_u32 v42, v40, 16, 1
	v_add_f32_e32 v41, 1.0, v108
	v_rcp_f32_e32 v41, v41
	v_add3_u32 v40, v40, v42, s29
	global_store_short_d16_hi v[132:133], v40, off offset:2048
	s_add_i32 s34, s34, 0x28000
	v_mul_f32_e32 v40, v44, v41
	s_waitcnt vmcnt(16)
	v_lshlrev_b32_e32 v41, 16, v107
	v_fma_f32 v42, v104, v41, v45
	v_mul_f32_e32 v41, 0x3d372713, v42
	v_mul_f32_e32 v41, v42, v41
	v_fma_f32 v41, v42, v41, v42
	v_mul_f32_e32 v41, 0x3fcc422a, v41
	v_mul_f32_e32 v41, 0xbfb8aa3b, v41
	v_exp_f32_e32 v41, v41
	v_bfe_u32 v43, v40, 16, 1
	v_add3_u32 v43, v40, v43, s29
	v_or_b32_e32 v40, 0x8000, v130
	v_add_f32_e32 v41, 1.0, v41
	v_rcp_f32_e32 v44, v41
	v_mov_b32_e32 v41, v131
	v_lshl_add_u64 v[40:41], v[62:63], 0, v[40:41]
	global_store_short_d16_hi v[40:41], v43, off
	s_waitcnt vmcnt(16)
	v_lshlrev_b32_e32 v41, 16, v106
	v_mul_f32_e32 v40, v42, v44
	v_fma_f32 v42, v104, v41, v46
	v_mul_f32_e32 v41, 0x3d372713, v42
	v_mul_f32_e32 v41, v42, v41
	v_fma_f32 v41, v42, v41, v42
	v_mul_f32_e32 v41, 0x3fcc422a, v41
	v_mul_f32_e32 v41, 0xbfb8aa3b, v41
	v_exp_f32_e32 v41, v41
	v_bfe_u32 v43, v40, 16, 1
	v_add3_u32 v43, v40, v43, s29
	v_or_b32_e32 v40, 0x8800, v130
	v_add_f32_e32 v41, 1.0, v41
	v_rcp_f32_e32 v44, v41
	v_mov_b32_e32 v41, v131
	v_lshl_add_u64 v[40:41], v[62:63], 0, v[40:41]
	global_store_short_d16_hi v[40:41], v43, off
	s_waitcnt vmcnt(16)
	v_lshlrev_b32_e32 v41, 16, v105
	v_fmac_f32_e32 v47, v104, v41
	v_mul_f32_e32 v41, 0x3d372713, v47
	v_mul_f32_e32 v41, v47, v41
	v_fma_f32 v41, v47, v41, v47
	v_mul_f32_e32 v41, 0x3fcc422a, v41
	v_mul_f32_e32 v41, 0xbfb8aa3b, v41
	v_exp_f32_e32 v41, v41
	v_mul_f32_e32 v40, v42, v44
	v_bfe_u32 v42, v40, 16, 1
	v_add3_u32 v42, v40, v42, s29
	v_add_f32_e32 v41, 1.0, v41
	v_rcp_f32_e32 v43, v41
	v_or_b32_e32 v40, 0x9000, v130
	v_mov_b32_e32 v41, v131
	v_lshl_add_u64 v[40:41], v[62:63], 0, v[40:41]
	global_store_short_d16_hi v[40:41], v42, off
	v_mul_f32_e32 v40, v47, v43
	v_bfe_u32 v41, v40, 16, 1
	v_or_b32_e32 v130, 0x9800, v130
	v_add3_u32 v42, v40, v41, s29
	v_lshl_add_u64 v[40:41], v[62:63], 0, v[130:131]
	global_store_short_d16_hi v[40:41], v42, off
	s_waitcnt vmcnt(16)
	v_mov_b64_e32 v[46:47], v[38:39]
	v_mov_b64_e32 v[42:43], v[34:35]
	s_cmp_eq_u32 s26, 0x400000
	s_waitcnt vmcnt(13)
	v_mov_b32_e32 v118, v117
	v_mov_b32_e32 v119, v111
	v_mov_b32_e32 v120, v110
	s_waitcnt vmcnt(12)
	v_mov_b32_e32 v109, v112
	s_waitcnt vmcnt(11)
	v_mov_b32_e32 v108, v113
	s_waitcnt vmcnt(10)
	v_mov_b32_e32 v107, v114
	s_waitcnt vmcnt(9)
	v_mov_b32_e32 v106, v115
	s_waitcnt vmcnt(8)
	v_mov_b32_e32 v105, v116
	v_mov_b64_e32 v[44:45], v[36:37]
	v_mov_b64_e32 v[40:41], v[32:33]
	s_cbranch_scc1 .LBB0_384
